# GEMM: phase prologue stages both K tiles before its first wait; first K pair after an epilogue waits vmcnt(24); M0 not saved around K-loop DMAs
# speedup vs baseline: 1.0075x; 1.0075x over previous
; #define PG8_STAGE(bufoff, gbase, voff) do { _Pragma("unroll") for (int _i = 0; _i < 2; ++_i) \
;         glds16((const void*)(gbase), (voff)[_i], (unsigned)__builtin_amdgcn_readfirstlane(lds0 + (bufoff) + ldsw + _i * 8192)); } while (0)
; #define PG8_WAIT_V(n) asm volatile("s_waitcnt vmcnt(" #n ")" ::: "memory")
; #define PG8_BAR __builtin_amdgcn_s_barrier()
; template <class Epi, class Sched, bool ALIGN_EPI = false, bool SP2 = false>
; __device__ __forceinline__ void gemm_phase(LAS unsigned char* lds, const Gemm g, const Sched& S, const Epi& E) {
;     ...
;     for (int i = 0; i < 2; ++i) { int R, C; stage_rc(tid * 16 + i * 8192, R, C); const int Rb = Epi::PERM ? ((R & ~31) + perm32(R & 31)) : R;
;         voffA[i] = (unsigned)(R * K + C) * 2u; voffB[i] = (unsigned)(Rb * K + C) * 2u; }
;     const size_t kstep = (size_t)(BK * 2);
;     const size_t hstep = (size_t)HALF * K * 2;
;     const size_t tstep = 2 * hstep;
;     const unsigned ldsw = (unsigned)wid * 1024u, lds0 = (unsigned)(uintptr_t)lds;
;     const int aoff = lds_byte(wr * 64 + fr, fq * 8), boff = lds_byte(wc * 32 + fr, fq * 8);
;     ...
;         PG8_STAGE(PG8_SB(0, 0), cB, voffB); PG8_STAGE(PG8_SB(0, 1), cB + hstep, voffB); PG8_STAGE(PG8_SA(0, 0), cA, voffA); PG8_STAGE(PG8_SA(0, 1), cA + hstep, voffA);
;         if (wr == 1) PG8_BAR;
;         PG8_WAIT_V(2); PG8_BAR;
;         PG8_STAGE(PG8_SB(1, 0), cB + kstep, voffB); PG8_STAGE(PG8_SA(1, 0), cA + kstep, voffA); PG8_STAGE(PG8_SB(1, 1), cB + hstep + kstep, voffB);
;         PG8_WAIT_V(6); PG8_BAR;
.LBB0_107:
	s_and_b64 s[10:11], s[16:17], exec
	v_readlane_b32 s10, v233, 51
	v_readlane_b32 s11, v233, 52
	s_cselect_b32 s24, s34, s10
	v_readlane_b32 s10, v232, 48
	s_cselect_b32 s25, s35, s11
	s_and_b32 s7, s10, 3
	s_lshl_b32 s10, s10, 7
	s_and_b32 s10, s10, 0x200
	v_readlane_b32 s12, v233, 8
	v_readlane_b32 s13, v233, 9
	s_add_u32 s10, s12, s10
	s_addc_u32 s11, s13, 0
	s_cmp_eq_u32 s7, 2
	s_cselect_b32 s31, s11, 0
	s_cselect_b32 s30, s10, 0
	s_cmp_lg_u64 s[30:31], 0
	v_bfe_u32 v4, v2, 4, 2
	s_cselect_b64 s[44:45], -1, 0
	s_and_b64 s[10:11], s[16:17], exec
	v_and_b32_e32 v3, 15, v2
	v_lshlrev_b32_e32 v6, 4, v4
	v_lshlrev_b32_e32 v2, 2, v2
	s_cselect_b32 s63, 12, 10
	s_and_b32 s64, s4, 3
	v_lshl_or_b32 v6, v3, 6, v6
	s_lshl_b32 s4, s5, 13
	v_and_b32_e32 v2, 32, v2
	v_bitop3_b32 v7, v6, s4, v2 bitop3:0xde
	s_lshl_b32 s4, s64, 12
	v_bitop3_b32 v2, v6, s4, v2 bitop3:0xde
	s_add_u32 s4, s82, 0x80
	v_lshl_or_b32 v151, s5, 6, v3
	s_addc_u32 s5, s83, 0
	s_add_i32 s65, s2, 0x18000
	s_mov_b32 s7, m0
	s_mov_b32 m0, s65
	s_nop 0
	global_load_lds_dwordx4 v148, s[4:5]
	s_mov_b32 m0, s7
	s_add_i32 s66, s2, 0x1a000
	s_mov_b32 s7, m0
	s_mov_b32 m0, s66
	s_nop 0
	global_load_lds_dwordx4 v150, s[4:5]
	s_mov_b32 m0, s7
	s_add_u32 s4, s22, 0x80
	s_addc_u32 s5, s23, 0
	s_add_i32 s67, s2, 0x8000
	s_mov_b32 s7, m0
	s_mov_b32 m0, s67
	s_nop 0
	global_load_lds_dwordx4 v0, s[4:5]
	s_mov_b32 m0, s7
	s_add_i32 s68, s2, 0xa000
	s_mov_b32 s7, m0
	s_mov_b32 m0, s68
	s_nop 0
	global_load_lds_dwordx4 v149, s[4:5]
	s_mov_b32 m0, s7
	s_add_u32 s4, s82, 0x40080
	s_addc_u32 s5, s83, 0
	s_add_i32 s69, s2, 0x1c000
	s_mov_b32 s7, m0
	s_mov_b32 m0, s69
	s_nop 0
	global_load_lds_dwordx4 v148, s[4:5]
	s_mov_b32 m0, s7
	s_add_i32 s70, s2, 0x1e000
	s_mov_b32 s7, m0
	s_mov_b32 m0, s70
	s_nop 0
	global_load_lds_dwordx4 v150, s[4:5]
	s_mov_b32 m0, s7
	s_waitcnt vmcnt(8)
	s_barrier
	s_waitcnt vmcnt(6)
	s_add_i32 s71, s2, 0xc000
	v_lshlrev_b32_e32 v5, 3, v4
	s_cmpk_lt_u32 s6, 0x100
	v_or_b32_e32 v3, v4, v3
	v_add_u32_e32 v2, 0, v2
	s_mov_b32 s62, 0
	v_lshl_or_b32 v152, s64, 5, v5
	s_cselect_b64 s[90:91], -1, 0
	v_cmp_eq_u32_e64 s[4:5], 0, v3
	s_bfe_u32 s72, s6, 0x10006
	v_add_u32_e32 v153, 0x10000, v2
	v_add_u32_e32 v154, 0x14000, v2
	v_add_u32_e32 v155, 0, v7
	v_add_u32_e32 v156, 0x18000, v2
	v_add_u32_e32 v157, 0x1c000, v2
	v_mov_b64_e32 v[130:131], s[96:97]
	v_readlane_b32 s40, v233, 45
	v_readlane_b32 s41, v233, 46
	s_barrier
	s_branch .LBB0_110

; #define PG8_STAGE(bufoff, gbase, voff) do { _Pragma("unroll") for (int _i = 0; _i < 2; ++_i) \
;         glds16((const void*)(gbase), (voff)[_i], (unsigned)__builtin_amdgcn_readfirstlane(lds0 + (bufoff) + ldsw + _i * 8192)); } while (0)
; #define PG8_LDA(dst, b, h) do { _Pragma("unroll") for (int m = 0; m < 4; ++m) _Pragma("unroll") for (int k = 0; k < 2; ++k) dst[m][k] = *(const LAS bf16x8*)(lds + PG8_SA(b, h) + aoff + m * 2048 + k * 1024); } while (0)
; #define PG8_LDB(dst, b, h) do { _Pragma("unroll") for (int n = 0; n < 2; ++n) _Pragma("unroll") for (int k = 0; k < 2; ++k) dst[n][k] = *(const LAS bf16x8*)(lds + PG8_SB(b, h) + boff + n * 2048 + k * 1024); } while (0)
; #define PG8_MMA(ai, bj, At, Bt) do { __builtin_amdgcn_s_setprio(1); _Pragma("unroll") for (int m = 0; m < 4; ++m) _Pragma("unroll") for (int n = 0; n < 2; ++n) _Pragma("unroll") for (int k = 0; k < 2; ++k) \
;         acc[ai][bj][m][n] = __builtin_amdgcn_mfma_f32_16x16x32_bf16(Bt[n][k], At[m][k], acc[ai][bj][m][n], 0, 0, 0); __builtin_amdgcn_s_setprio(0); } while (0)
; #define PG8_WAIT_V(n) asm volatile("s_waitcnt vmcnt(" #n ")" ::: "memory")
; #define PG8_WAIT_L(n) asm volatile("s_waitcnt lgkmcnt(" #n ")" ::: "memory")
; #define PG8_BAR __builtin_amdgcn_s_barrier()
; #define PG8_SCHED __builtin_amdgcn_sched_barrier(0)
; template <class Epi, class Sched, bool ALIGN_EPI = false, bool SP2 = false>
; __device__ __forceinline__ void gemm_phase(LAS unsigned char* lds, const Gemm g, const Sched& S, const Epi& E) {
;     ...
;             const char* a2 = last ? nA : cA + (size_t)(t + 2) * kstep; const char* b2 = last ? nB : cB + (size_t)(t + 2) * kstep;
;     ...
;             PG8_LDB(B0, 0, 0); PG8_LDB(B1, 0, 1); PG8_SCHED; PG8_LDA(At, 0, 0); PG8_STAGE(PG8_SA(1, 1), a1 + hstep, voffA);
;             PG8_WAIT_V(8); PG8_WAIT_L(0); PG8_BAR; PG8_MMA(0, 0, At, B0); PG8_MMA(0, 1, At, B1); PG8_BAR; PG8_SCHED;
;             PG8_LDA(At, 0, 1); PG8_STAGE(PG8_SB(0, 0), b2, voffB); PG8_STAGE(PG8_SB(0, 1), b2 + hstep, voffB); PG8_STAGE(PG8_SA(0, 0), a2, voffA);
;             PG8_WAIT_V(8); PG8_WAIT_L(0); PG8_BAR; PG8_MMA(1, 0, At, B0); PG8_MMA(1, 1, At, B1); PG8_BAR; PG8_SCHED;
.LBB0_117:
	ds_read_b128 v[132:135], v153
	ds_read_b128 v[136:139], v153 offset:1024
	ds_read_b128 v[142:145], v153 offset:2048
	ds_read_b128 v[168:171], v153 offset:3072
	ds_read_b128 v[172:175], v154
	ds_read_b128 v[176:179], v154 offset:1024
	ds_read_b128 v[180:183], v154 offset:2048
	ds_read_b128 v[184:187], v154 offset:3072
	s_add_u32 vcc_lo, s22, 0x100
	s_addc_u32 vcc_hi, s23, 0
	s_cmp_eq_u32 s77, 12
	s_cselect_b32 s10, s73, vcc_lo
	s_cselect_b32 s11, s29, vcc_hi
	s_cselect_b32 s46, s74, s75
	s_cselect_b32 s47, s13, s76
	s_add_u32 s82, s10, 0x80
	s_addc_u32 s83, s11, 0
	ds_read_b128 v[188:191], v155
	ds_read_b128 v[192:195], v155 offset:1024
	ds_read_b128 v[196:199], v155 offset:2048
	ds_read_b128 v[200:203], v155 offset:3072
	ds_read_b128 v[204:207], v155 offset:4096
	ds_read_b128 v[208:211], v155 offset:5120
	ds_read_b128 v[212:215], v155 offset:6144
	ds_read_b128 v[216:219], v155 offset:7168
	s_add_u32 s22, s22, 0x40080
	s_addc_u32 s23, s23, 0
	s_mov_b32 m0, s71
	s_nop 0
	global_load_lds_dwordx4 v0, s[22:23]
	s_add_i32 s26, s2, 0xe000
	s_mov_b32 m0, s26
	s_nop 0
	global_load_lds_dwordx4 v149, s[22:23]
	s_cmp_lg_u32 s77, -2
	s_cbranch_scc1 .Lkw8_1
	s_cmp_lt_u32 s62, 2
	s_cbranch_scc1 .Lkw8_1
	s_waitcnt vmcnt(24)
	s_branch .Lkwj_1
.Lkw8_1:
	s_waitcnt vmcnt(8)
.Lkwj_1:
	s_waitcnt lgkmcnt(0)
	s_barrier
	s_setprio 1
	s_waitcnt lgkmcnt(7)
	v_mfma_f32_16x16x32_bf16 v[126:129], v[132:135], v[188:191], v[126:129]
	v_mfma_f32_16x16x32_bf16 v[122:125], v[142:145], v[188:191], v[122:125]
	s_waitcnt lgkmcnt(5)
	v_mfma_f32_16x16x32_bf16 v[118:121], v[132:135], v[196:199], v[118:121]
	v_mfma_f32_16x16x32_bf16 v[110:113], v[142:145], v[196:199], v[110:113]
	s_waitcnt lgkmcnt(3)
	v_mfma_f32_16x16x32_bf16 v[102:105], v[132:135], v[204:207], v[102:105]
	v_mfma_f32_16x16x32_bf16 v[94:97], v[142:145], v[204:207], v[94:97]
	s_waitcnt lgkmcnt(1)
	v_mfma_f32_16x16x32_bf16 v[86:89], v[132:135], v[212:215], v[86:89]
	v_mfma_f32_16x16x32_bf16 v[78:81], v[142:145], v[212:215], v[78:81]
	v_mfma_f32_16x16x32_bf16 v[126:129], v[136:139], v[192:195], v[126:129]
	v_mfma_f32_16x16x32_bf16 v[122:125], v[168:171], v[192:195], v[122:125]
	v_mfma_f32_16x16x32_bf16 v[118:121], v[136:139], v[200:203], v[118:121]
	v_mfma_f32_16x16x32_bf16 v[110:113], v[168:171], v[200:203], v[110:113]
	v_mfma_f32_16x16x32_bf16 v[102:105], v[136:139], v[208:211], v[102:105]
	v_mfma_f32_16x16x32_bf16 v[94:97], v[168:171], v[208:211], v[94:97]
	s_waitcnt lgkmcnt(0)
	v_mfma_f32_16x16x32_bf16 v[86:89], v[136:139], v[216:219], v[86:89]
	v_mfma_f32_16x16x32_bf16 v[78:81], v[168:171], v[216:219], v[78:81]
	s_setprio 0
	s_setprio 1
	v_mfma_f32_16x16x32_bf16 v[114:117], v[172:175], v[188:191], v[114:117]
	v_mfma_f32_16x16x32_bf16 v[106:109], v[180:183], v[188:191], v[106:109]
	v_mfma_f32_16x16x32_bf16 v[98:101], v[172:175], v[196:199], v[98:101]
	v_mfma_f32_16x16x32_bf16 v[90:93], v[180:183], v[196:199], v[90:93]
	v_mfma_f32_16x16x32_bf16 v[82:85], v[172:175], v[204:207], v[82:85]
	v_mfma_f32_16x16x32_bf16 v[74:77], v[180:183], v[204:207], v[74:77]
	v_mfma_f32_16x16x32_bf16 v[70:73], v[172:175], v[212:215], v[70:73]
	v_mfma_f32_16x16x32_bf16 v[66:69], v[180:183], v[212:215], v[66:69]
	v_mfma_f32_16x16x32_bf16 v[114:117], v[176:179], v[192:195], v[114:117]
	v_mfma_f32_16x16x32_bf16 v[106:109], v[184:187], v[192:195], v[106:109]
	v_mfma_f32_16x16x32_bf16 v[98:101], v[176:179], v[200:203], v[98:101]
	v_mfma_f32_16x16x32_bf16 v[90:93], v[184:187], v[200:203], v[90:93]
	v_mfma_f32_16x16x32_bf16 v[82:85], v[176:179], v[208:211], v[82:85]
	v_mfma_f32_16x16x32_bf16 v[74:77], v[184:187], v[208:211], v[74:77]
	v_mfma_f32_16x16x32_bf16 v[70:73], v[176:179], v[216:219], v[70:73]
	v_mfma_f32_16x16x32_bf16 v[66:69], v[184:187], v[216:219], v[66:69]
	s_setprio 0
	s_barrier
	ds_read_b128 v[188:191], v155 offset:16384
	ds_read_b128 v[192:195], v155 offset:17408
	ds_read_b128 v[196:199], v155 offset:18432
	ds_read_b128 v[200:203], v155 offset:19456
	ds_read_b128 v[204:207], v155 offset:20480
	ds_read_b128 v[208:211], v155 offset:21504
	ds_read_b128 v[212:215], v155 offset:22528
	ds_read_b128 v[216:219], v155 offset:23552
	s_mov_b32 m0, s21
	s_nop 0
	global_load_lds_dwordx4 v148, s[46:47]
	s_nop 0
	s_mov_b32 m0, s56
	s_nop 0
	global_load_lds_dwordx4 v150, s[46:47]
	s_add_u32 s22, s46, 0x40000
	s_addc_u32 s23, s47, 0
	s_mov_b32 m0, s57
	s_nop 0
	global_load_lds_dwordx4 v148, s[22:23]
	s_nop 0
	s_mov_b32 m0, s58
	s_nop 0
	global_load_lds_dwordx4 v150, s[22:23]
	s_mov_b32 m0, s2
	s_nop 0
	global_load_lds_dwordx4 v0, s[10:11]
	s_nop 0
	s_mov_b32 m0, s59
	s_nop 0
	global_load_lds_dwordx4 v149, s[10:11]
	s_cmp_lg_u32 s77, -2
	s_cbranch_scc1 .Lkw8_2
	s_cmp_lt_u32 s62, 2
	s_cbranch_scc1 .Lkw8_2
	s_waitcnt vmcnt(24)
	s_branch .Lkwj_2

; #define PG8_STAGE(bufoff, gbase, voff) do { _Pragma("unroll") for (int _i = 0; _i < 2; ++_i) \
;         glds16((const void*)(gbase), (voff)[_i], (unsigned)__builtin_amdgcn_readfirstlane(lds0 + (bufoff) + ldsw + _i * 8192)); } while (0)
; #define PG8_LDA(dst, b, h) do { _Pragma("unroll") for (int m = 0; m < 4; ++m) _Pragma("unroll") for (int k = 0; k < 2; ++k) dst[m][k] = *(const LAS bf16x8*)(lds + PG8_SA(b, h) + aoff + m * 2048 + k * 1024); } while (0)
; #define PG8_LDB(dst, b, h) do { _Pragma("unroll") for (int n = 0; n < 2; ++n) _Pragma("unroll") for (int k = 0; k < 2; ++k) dst[n][k] = *(const LAS bf16x8*)(lds + PG8_SB(b, h) + boff + n * 2048 + k * 1024); } while (0)
; #define PG8_MMA(ai, bj, At, Bt) do { __builtin_amdgcn_s_setprio(1); _Pragma("unroll") for (int m = 0; m < 4; ++m) _Pragma("unroll") for (int n = 0; n < 2; ++n) _Pragma("unroll") for (int k = 0; k < 2; ++k) \
;         acc[ai][bj][m][n] = __builtin_amdgcn_mfma_f32_16x16x32_bf16(Bt[n][k], At[m][k], acc[ai][bj][m][n], 0, 0, 0); __builtin_amdgcn_s_setprio(0); } while (0)
; #define PG8_WAIT_V(n) asm volatile("s_waitcnt vmcnt(" #n ")" ::: "memory")
; #define PG8_WAIT_L(n) asm volatile("s_waitcnt lgkmcnt(" #n ")" ::: "memory")
; #define PG8_BAR __builtin_amdgcn_s_barrier()
; #define PG8_SCHED __builtin_amdgcn_sched_barrier(0)
; template <class Epi, class Sched, bool ALIGN_EPI = false, bool SP2 = false>
; __device__ __forceinline__ void gemm_phase(LAS unsigned char* lds, const Gemm g, const Sched& S, const Epi& E) {
;     ...
;             PG8_WAIT_V(8); PG8_WAIT_L(0); PG8_BAR; PG8_MMA(1, 0, At, B0); PG8_MMA(1, 1, At, B1); PG8_BAR; PG8_SCHED;
;             PG8_LDB(B0, 1, 0); PG8_LDB(B1, 1, 1); PG8_SCHED; PG8_LDA(At, 1, 0); PG8_STAGE(PG8_SA(0, 1), a2 + hstep, voffA);
;             PG8_WAIT_V(8); PG8_WAIT_L(0); PG8_BAR; PG8_MMA(0, 0, At, B0); PG8_MMA(0, 1, At, B1); PG8_BAR; PG8_SCHED;
.Lkwj_2:
	s_waitcnt lgkmcnt(0)
	s_barrier
	s_setprio 1
	s_waitcnt lgkmcnt(7)
	v_mfma_f32_16x16x32_bf16 v[62:65], v[132:135], v[188:191], v[62:65]
	v_mfma_f32_16x16x32_bf16 v[58:61], v[142:145], v[188:191], v[58:61]
	s_waitcnt lgkmcnt(5)
	v_mfma_f32_16x16x32_bf16 v[54:57], v[132:135], v[196:199], v[54:57]
	v_mfma_f32_16x16x32_bf16 v[46:49], v[142:145], v[196:199], v[46:49]
	s_waitcnt lgkmcnt(3)
	v_mfma_f32_16x16x32_bf16 v[38:41], v[132:135], v[204:207], v[38:41]
	v_mfma_f32_16x16x32_bf16 v[30:33], v[142:145], v[204:207], v[30:33]
	s_waitcnt lgkmcnt(1)
	v_mfma_f32_16x16x32_bf16 v[22:25], v[132:135], v[212:215], v[22:25]
	v_mfma_f32_16x16x32_bf16 v[14:17], v[142:145], v[212:215], v[14:17]
	v_mfma_f32_16x16x32_bf16 v[62:65], v[136:139], v[192:195], v[62:65]
	v_mfma_f32_16x16x32_bf16 v[58:61], v[168:171], v[192:195], v[58:61]
	v_mfma_f32_16x16x32_bf16 v[54:57], v[136:139], v[200:203], v[54:57]
	v_mfma_f32_16x16x32_bf16 v[46:49], v[168:171], v[200:203], v[46:49]
	v_mfma_f32_16x16x32_bf16 v[38:41], v[136:139], v[208:211], v[38:41]
	v_mfma_f32_16x16x32_bf16 v[30:33], v[168:171], v[208:211], v[30:33]
	s_waitcnt lgkmcnt(0)
	v_mfma_f32_16x16x32_bf16 v[22:25], v[136:139], v[216:219], v[22:25]
	v_mfma_f32_16x16x32_bf16 v[14:17], v[168:171], v[216:219], v[14:17]
	s_setprio 0
	s_setprio 1
	v_mfma_f32_16x16x32_bf16 v[50:53], v[172:175], v[188:191], v[50:53]
	v_mfma_f32_16x16x32_bf16 v[42:45], v[180:183], v[188:191], v[42:45]
	v_mfma_f32_16x16x32_bf16 v[34:37], v[172:175], v[196:199], v[34:37]
	v_mfma_f32_16x16x32_bf16 v[26:29], v[180:183], v[196:199], v[26:29]
	v_mfma_f32_16x16x32_bf16 v[18:21], v[172:175], v[204:207], v[18:21]
	v_mfma_f32_16x16x32_bf16 v[10:13], v[180:183], v[204:207], v[10:13]
	v_mfma_f32_16x16x32_bf16 v[6:9], v[172:175], v[212:215], v[6:9]
	v_mfma_f32_16x16x32_bf16 v[2:5], v[180:183], v[212:215], v[2:5]
	v_mfma_f32_16x16x32_bf16 v[50:53], v[176:179], v[192:195], v[50:53]
	v_mfma_f32_16x16x32_bf16 v[42:45], v[184:187], v[192:195], v[42:45]
	v_mfma_f32_16x16x32_bf16 v[34:37], v[176:179], v[200:203], v[34:37]
	v_mfma_f32_16x16x32_bf16 v[26:29], v[184:187], v[200:203], v[26:29]
	v_mfma_f32_16x16x32_bf16 v[18:21], v[176:179], v[208:211], v[18:21]
	v_mfma_f32_16x16x32_bf16 v[10:13], v[184:187], v[208:211], v[10:13]
	v_mfma_f32_16x16x32_bf16 v[6:9], v[176:179], v[216:219], v[6:9]
	v_mfma_f32_16x16x32_bf16 v[2:5], v[184:187], v[216:219], v[2:5]
	s_setprio 0
	s_barrier
	ds_read_b128 v[132:135], v156
	ds_read_b128 v[136:139], v156 offset:1024
	ds_read_b128 v[142:145], v156 offset:2048
	ds_read_b128 v[168:171], v156 offset:3072
	ds_read_b128 v[172:175], v157
	ds_read_b128 v[176:179], v157 offset:1024
	ds_read_b128 v[180:183], v157 offset:2048
	ds_read_b128 v[184:187], v157 offset:3072
	ds_read_b128 v[188:191], v155 offset:32768
	ds_read_b128 v[192:195], v155 offset:33792
	ds_read_b128 v[196:199], v155 offset:34816
	ds_read_b128 v[200:203], v155 offset:35840
	ds_read_b128 v[204:207], v155 offset:36864
	ds_read_b128 v[208:211], v155 offset:37888
	ds_read_b128 v[212:215], v155 offset:38912
	ds_read_b128 v[216:219], v155 offset:39936
	s_add_u32 s10, s10, 0x40000
	s_addc_u32 s11, s11, 0
	s_mov_b32 m0, s60
	s_nop 0
	global_load_lds_dwordx4 v0, s[10:11]
	s_nop 0
	s_mov_b32 m0, s61
	s_nop 0
	global_load_lds_dwordx4 v149, s[10:11]
	s_waitcnt vmcnt(8)
	s_waitcnt lgkmcnt(0)
	s_barrier
	s_setprio 1
	s_waitcnt lgkmcnt(7)
	v_mfma_f32_16x16x32_bf16 v[126:129], v[132:135], v[188:191], v[126:129]
	v_mfma_f32_16x16x32_bf16 v[122:125], v[142:145], v[188:191], v[122:125]
	s_waitcnt lgkmcnt(5)
	v_mfma_f32_16x16x32_bf16 v[118:121], v[132:135], v[196:199], v[118:121]
	v_mfma_f32_16x16x32_bf16 v[110:113], v[142:145], v[196:199], v[110:113]
	s_waitcnt lgkmcnt(3)
	v_mfma_f32_16x16x32_bf16 v[102:105], v[132:135], v[204:207], v[102:105]
	v_mfma_f32_16x16x32_bf16 v[94:97], v[142:145], v[204:207], v[94:97]
	s_waitcnt lgkmcnt(1)
	v_mfma_f32_16x16x32_bf16 v[86:89], v[132:135], v[212:215], v[86:89]
	v_mfma_f32_16x16x32_bf16 v[78:81], v[142:145], v[212:215], v[78:81]
	v_mfma_f32_16x16x32_bf16 v[126:129], v[136:139], v[192:195], v[126:129]
	v_mfma_f32_16x16x32_bf16 v[122:125], v[168:171], v[192:195], v[122:125]
	v_mfma_f32_16x16x32_bf16 v[118:121], v[136:139], v[200:203], v[118:121]
	v_mfma_f32_16x16x32_bf16 v[110:113], v[168:171], v[200:203], v[110:113]
	v_mfma_f32_16x16x32_bf16 v[102:105], v[136:139], v[208:211], v[102:105]
	v_mfma_f32_16x16x32_bf16 v[94:97], v[168:171], v[208:211], v[94:97]
	s_waitcnt lgkmcnt(0)
	v_mfma_f32_16x16x32_bf16 v[86:89], v[136:139], v[216:219], v[86:89]
	v_mfma_f32_16x16x32_bf16 v[78:81], v[168:171], v[216:219], v[78:81]
	s_setprio 0
	s_setprio 1
	v_mfma_f32_16x16x32_bf16 v[114:117], v[172:175], v[188:191], v[114:117]
	v_mfma_f32_16x16x32_bf16 v[106:109], v[180:183], v[188:191], v[106:109]
	v_mfma_f32_16x16x32_bf16 v[98:101], v[172:175], v[196:199], v[98:101]
	v_mfma_f32_16x16x32_bf16 v[90:93], v[180:183], v[196:199], v[90:93]
	v_mfma_f32_16x16x32_bf16 v[82:85], v[172:175], v[204:207], v[82:85]
	v_mfma_f32_16x16x32_bf16 v[74:77], v[180:183], v[204:207], v[74:77]
	v_mfma_f32_16x16x32_bf16 v[70:73], v[172:175], v[212:215], v[70:73]
	v_mfma_f32_16x16x32_bf16 v[66:69], v[180:183], v[212:215], v[66:69]
	v_mfma_f32_16x16x32_bf16 v[114:117], v[176:179], v[192:195], v[114:117]
	v_mfma_f32_16x16x32_bf16 v[106:109], v[184:187], v[192:195], v[106:109]
	v_mfma_f32_16x16x32_bf16 v[98:101], v[176:179], v[200:203], v[98:101]
	v_mfma_f32_16x16x32_bf16 v[90:93], v[184:187], v[200:203], v[90:93]
	v_mfma_f32_16x16x32_bf16 v[82:85], v[176:179], v[208:211], v[82:85]
	v_mfma_f32_16x16x32_bf16 v[74:77], v[184:187], v[208:211], v[74:77]
	v_mfma_f32_16x16x32_bf16 v[70:73], v[176:179], v[216:219], v[70:73]
	v_mfma_f32_16x16x32_bf16 v[66:69], v[184:187], v[216:219], v[66:69]
	s_setprio 0
	s_barrier
; #define PG8_STAGE(bufoff, gbase, voff) do { _Pragma("unroll") for (int _i = 0; _i < 2; ++_i) \
;         glds16((const void*)(gbase), (voff)[_i], (unsigned)__builtin_amdgcn_readfirstlane(lds0 + (bufoff) + ldsw + _i * 8192)); } while (0)
; #define PG8_LDA(dst, b, h) do { _Pragma("unroll") for (int m = 0; m < 4; ++m) _Pragma("unroll") for (int k = 0; k < 2; ++k) dst[m][k] = *(const LAS bf16x8*)(lds + PG8_SA(b, h) + aoff + m * 2048 + k * 1024); } while (0)
; #define PG8_MMA(ai, bj, At, Bt) do { __builtin_amdgcn_s_setprio(1); _Pragma("unroll") for (int m = 0; m < 4; ++m) _Pragma("unroll") for (int n = 0; n < 2; ++n) _Pragma("unroll") for (int k = 0; k < 2; ++k) \
;         acc[ai][bj][m][n] = __builtin_amdgcn_mfma_f32_16x16x32_bf16(Bt[n][k], At[m][k], acc[ai][bj][m][n], 0, 0, 0); __builtin_amdgcn_s_setprio(0); } while (0)
; #define PG8_WAIT_V(n) asm volatile("s_waitcnt vmcnt(" #n ")" ::: "memory")
; #define PG8_WAIT_L(n) asm volatile("s_waitcnt lgkmcnt(" #n ")" ::: "memory")
; #define PG8_BAR __builtin_amdgcn_s_barrier()
; #define PG8_SCHED __builtin_amdgcn_sched_barrier(0)
; template <class Epi, class Sched, bool ALIGN_EPI = false, bool SP2 = false>
; __device__ __forceinline__ void gemm_phase(LAS unsigned char* lds, const Gemm g, const Sched& S, const Epi& E) {
;     ...
;             PG8_LDA(At, 1, 1); PG8_STAGE(PG8_SB(1, 0), b3, voffB); PG8_STAGE(PG8_SB(1, 1), b3 + hstep, voffB); PG8_STAGE(PG8_SA(1, 0), a3, voffA);
;             PG8_WAIT_V(8); PG8_WAIT_L(0); PG8_BAR; PG8_MMA(1, 0, At, B0); PG8_MMA(1, 1, At, B1); PG8_BAR; PG8_SCHED;
	ds_read_b128 v[188:191], v155 offset:49152
	ds_read_b128 v[192:195], v155 offset:50176
	ds_read_b128 v[196:199], v155 offset:51200
	ds_read_b128 v[200:203], v155 offset:52224
	ds_read_b128 v[204:207], v155 offset:53248
	ds_read_b128 v[208:211], v155 offset:54272
	ds_read_b128 v[212:215], v155 offset:55296
	ds_read_b128 v[216:219], v155 offset:56320
	s_add_u32 s10, s46, 0x80
	s_addc_u32 s11, s47, 0
	s_mov_b32 m0, s65
	s_nop 0
	global_load_lds_dwordx4 v148, s[10:11]
	s_nop 0
	s_mov_b32 m0, s66
	s_nop 0
	global_load_lds_dwordx4 v150, s[10:11]
	s_add_u32 s10, s46, 0x40080
	s_addc_u32 s11, s47, 0
	s_mov_b32 m0, s69
	s_nop 0
	global_load_lds_dwordx4 v148, s[10:11]
	s_nop 0
	s_mov_b32 m0, s70
	s_nop 0
	global_load_lds_dwordx4 v150, s[10:11]
	s_mov_b32 m0, s67
	s_nop 0
	global_load_lds_dwordx4 v0, s[82:83]
	s_nop 0
	s_mov_b32 m0, s68
	s_nop 0
	global_load_lds_dwordx4 v149, s[82:83]
	s_waitcnt vmcnt(8)
	s_waitcnt lgkmcnt(0)
	s_barrier
	s_setprio 1
	s_waitcnt lgkmcnt(7)
	v_mfma_f32_16x16x32_bf16 v[62:65], v[132:135], v[188:191], v[62:65]
	v_mfma_f32_16x16x32_bf16 v[58:61], v[142:145], v[188:191], v[58:61]
	s_waitcnt lgkmcnt(5)
	v_mfma_f32_16x16x32_bf16 v[54:57], v[132:135], v[196:199], v[54:57]
	v_mfma_f32_16x16x32_bf16 v[46:49], v[142:145], v[196:199], v[46:49]
	s_waitcnt lgkmcnt(3)
	v_mfma_f32_16x16x32_bf16 v[38:41], v[132:135], v[204:207], v[38:41]
	v_mfma_f32_16x16x32_bf16 v[30:33], v[142:145], v[204:207], v[30:33]
	s_waitcnt lgkmcnt(1)
	v_mfma_f32_16x16x32_bf16 v[22:25], v[132:135], v[212:215], v[22:25]
	v_mfma_f32_16x16x32_bf16 v[14:17], v[142:145], v[212:215], v[14:17]
	v_mfma_f32_16x16x32_bf16 v[62:65], v[136:139], v[192:195], v[62:65]
	v_mfma_f32_16x16x32_bf16 v[58:61], v[168:171], v[192:195], v[58:61]
	v_mfma_f32_16x16x32_bf16 v[54:57], v[136:139], v[200:203], v[54:57]
	v_mfma_f32_16x16x32_bf16 v[46:49], v[168:171], v[200:203], v[46:49]
	v_mfma_f32_16x16x32_bf16 v[38:41], v[136:139], v[208:211], v[38:41]
	v_mfma_f32_16x16x32_bf16 v[30:33], v[168:171], v[208:211], v[30:33]
	s_waitcnt lgkmcnt(0)
	v_mfma_f32_16x16x32_bf16 v[22:25], v[136:139], v[216:219], v[22:25]
	v_mfma_f32_16x16x32_bf16 v[14:17], v[168:171], v[216:219], v[14:17]
	s_setprio 0
	s_setprio 1
	v_mfma_f32_16x16x32_bf16 v[50:53], v[172:175], v[188:191], v[50:53]
	v_mfma_f32_16x16x32_bf16 v[42:45], v[180:183], v[188:191], v[42:45]
	v_mfma_f32_16x16x32_bf16 v[34:37], v[172:175], v[196:199], v[34:37]
	v_mfma_f32_16x16x32_bf16 v[26:29], v[180:183], v[196:199], v[26:29]
	v_mfma_f32_16x16x32_bf16 v[18:21], v[172:175], v[204:207], v[18:21]
	v_mfma_f32_16x16x32_bf16 v[10:13], v[180:183], v[204:207], v[10:13]
	v_mfma_f32_16x16x32_bf16 v[6:9], v[172:175], v[212:215], v[6:9]
	v_mfma_f32_16x16x32_bf16 v[2:5], v[180:183], v[212:215], v[2:5]
	v_mfma_f32_16x16x32_bf16 v[50:53], v[176:179], v[192:195], v[50:53]
	v_mfma_f32_16x16x32_bf16 v[42:45], v[184:187], v[192:195], v[42:45]
	v_mfma_f32_16x16x32_bf16 v[34:37], v[176:179], v[200:203], v[34:37]
	v_mfma_f32_16x16x32_bf16 v[26:29], v[184:187], v[200:203], v[26:29]
	v_mfma_f32_16x16x32_bf16 v[18:21], v[176:179], v[208:211], v[18:21]
	v_mfma_f32_16x16x32_bf16 v[10:13], v[184:187], v[208:211], v[10:13]
	v_mfma_f32_16x16x32_bf16 v[6:9], v[176:179], v[216:219], v[6:9]
	v_mfma_f32_16x16x32_bf16 v[2:5], v[184:187], v[216:219], v[2:5]
	s_setprio 0
	s_barrier
	s_add_i32 s77, s77, 2
	s_add_u32 s75, s75, 0x100
	s_addc_u32 s76, s76, 0
	s_cmp_gt_u32 s77, 13
	s_mov_b64 s[22:23], vcc
	s_cbranch_scc0 .LBB0_117
	s_and_b64 vcc, exec, s[90:91]
	s_cbranch_vccz .LBB0_120
